# v41 + P0 folded odd out-proj tiles: scaled w_out rows held in 128 VGPRs, pool_w rows by scalar loads (same fma order)
# baseline (speedup 1.0000x reference)
.Lwf_fold:
	v_and_b32_e32 v29, 63, v155
	v_lshrrev_b32_e32 v24, 6, v155
	v_lshlrev_b32_e32 v26, 2, v29
	v_lshlrev_b32_e32 v29, 1, v29
	v_readfirstlane_b32 s58, v24
	s_add_i32 s8, s89, 0xfffffe80
	s_lshr_b32 s30, s8, 7
	s_and_b32 s8, s8, 0x7f
	s_and_b32 s9, s8, 7
	s_lshr_b32 s8, s8, 3
	s_mul_i32 s59, s30, 48
	s_add_u32 s10, s0, s59
	s_addc_u32 s11, s1, 0
	s_load_dwordx2 s[56:57], s[10:11], 0x100
	s_load_dwordx2 s[54:55], s[10:11], 0x110
	s_load_dwordx2 s[90:91], s[10:11], 0x118
	s_load_dwordx2 vcc, s[0:1], 0xf8
	s_lshl_b32 s58, s58, 4
	s_waitcnt lgkmcnt(0)
	s_lshl_b32 s59, s30, 2
	s_add_i32 s59, s59, s9
	s_lshl_b32 s10, s59, 7
	s_add_i32 s10, s10, s58
	s_lshl_b32 s10, s10, 9
	s_add_u32 s52, s24, s10
	s_addc_u32 s53, s25, 0
	s_lshl_b32 s10, s59, 9
	s_add_u32 s6, s26, s10
	s_addc_u32 s7, s27, 0
	s_load_dwordx16 s[36:51], s[6:7], 0x0
	s_lshl_b32 s10, s9, 7
	s_add_i32 s11, s10, s58
	s_mul_i32 s10, s10, s91
	s_lshl_b32 s59, s8, 6
	s_add_i32 s10, s10, s59
	s_lshl_b32 s10, s10, 2
	s_add_u32 s56, s56, s10
	s_addc_u32 s57, s57, 0
	s_mul_i32 s10, s59, s90
	s_add_i32 s10, s10, s11
	s_lshl_b32 s10, s10, 1
	s_add_u32 s54, s54, s10
	s_addc_u32 s55, s55, 0
	s_add_u32 s54, s54, vcc_lo
	s_addc_u32 s55, s55, vcc_hi
	v_mul_u32_u24_e32 v27, s90, v29
	s_lshl_b32 s91, s91, 2
	global_load_dword v46, v26, s[56:57]
	s_add_u32 s56, s56, s91
	s_addc_u32 s57, s57, 0
	global_load_dword v47, v26, s[56:57]
	s_add_u32 s56, s56, s91
	s_addc_u32 s57, s57, 0
	global_load_dword v48, v26, s[56:57]
	s_add_u32 s56, s56, s91
	s_addc_u32 s57, s57, 0
	global_load_dword v49, v26, s[56:57]
	s_add_u32 s56, s56, s91
	s_addc_u32 s57, s57, 0
	global_load_dword v50, v26, s[56:57]
	s_add_u32 s56, s56, s91
	s_addc_u32 s57, s57, 0
	global_load_dword v51, v26, s[56:57]
	s_add_u32 s56, s56, s91
	s_addc_u32 s57, s57, 0
	global_load_dword v52, v26, s[56:57]
	s_add_u32 s56, s56, s91
	s_addc_u32 s57, s57, 0
	global_load_dword v53, v26, s[56:57]
	s_add_u32 s56, s56, s91
	s_addc_u32 s57, s57, 0
	global_load_dword v54, v26, s[56:57]
	s_add_u32 s56, s56, s91
	s_addc_u32 s57, s57, 0
	global_load_dword v55, v26, s[56:57]
	s_add_u32 s56, s56, s91
	s_addc_u32 s57, s57, 0
	global_load_dword v56, v26, s[56:57]
	s_add_u32 s56, s56, s91
	s_addc_u32 s57, s57, 0
	global_load_dword v57, v26, s[56:57]
	s_add_u32 s56, s56, s91
	s_addc_u32 s57, s57, 0
	global_load_dword v58, v26, s[56:57]
	s_add_u32 s56, s56, s91
	s_addc_u32 s57, s57, 0
	global_load_dword v59, v26, s[56:57]
	s_add_u32 s56, s56, s91
	s_addc_u32 s57, s57, 0
	global_load_dword v60, v26, s[56:57]
	s_add_u32 s56, s56, s91
	s_addc_u32 s57, s57, 0
	global_load_dword v61, v26, s[56:57]
	s_add_u32 s56, s56, s91
	s_addc_u32 s57, s57, 0
	s_load_dwordx16 s[68:83], s[6:7], 0x40
	global_load_dword v62, v26, s[56:57]
	s_add_u32 s56, s56, s91
	s_addc_u32 s57, s57, 0
	global_load_dword v63, v26, s[56:57]
	s_add_u32 s56, s56, s91
	s_addc_u32 s57, s57, 0
	global_load_dword v64, v26, s[56:57]
	s_add_u32 s56, s56, s91
	s_addc_u32 s57, s57, 0
	global_load_dword v65, v26, s[56:57]
	s_add_u32 s56, s56, s91
	s_addc_u32 s57, s57, 0
	global_load_dword v66, v26, s[56:57]
	s_add_u32 s56, s56, s91
	s_addc_u32 s57, s57, 0
	global_load_dword v67, v26, s[56:57]
	s_add_u32 s56, s56, s91
	s_addc_u32 s57, s57, 0
	global_load_dword v68, v26, s[56:57]
	s_add_u32 s56, s56, s91
	s_addc_u32 s57, s57, 0
	global_load_dword v69, v26, s[56:57]
	s_add_u32 s56, s56, s91
	s_addc_u32 s57, s57, 0
	global_load_dword v70, v26, s[56:57]
	s_add_u32 s56, s56, s91
	s_addc_u32 s57, s57, 0
	global_load_dword v71, v26, s[56:57]
	s_add_u32 s56, s56, s91
	s_addc_u32 s57, s57, 0
	global_load_dword v72, v26, s[56:57]
	s_add_u32 s56, s56, s91
	s_addc_u32 s57, s57, 0
	global_load_dword v73, v26, s[56:57]
	s_add_u32 s56, s56, s91
	s_addc_u32 s57, s57, 0
	global_load_dword v74, v26, s[56:57]
	s_add_u32 s56, s56, s91
	s_addc_u32 s57, s57, 0
	global_load_dword v75, v26, s[56:57]
	s_add_u32 s56, s56, s91
	s_addc_u32 s57, s57, 0
	global_load_dword v76, v26, s[56:57]
	s_add_u32 s56, s56, s91
	s_addc_u32 s57, s57, 0
	global_load_dword v77, v26, s[56:57]
	s_add_u32 s56, s56, s91
	s_addc_u32 s57, s57, 0
	global_load_dword v78, v26, s[56:57]
	s_add_u32 s56, s56, s91
	s_addc_u32 s57, s57, 0
	global_load_dword v79, v26, s[56:57]
	s_add_u32 s56, s56, s91
	s_addc_u32 s57, s57, 0
	global_load_dword v80, v26, s[56:57]
	s_add_u32 s56, s56, s91
	s_addc_u32 s57, s57, 0
	global_load_dword v81, v26, s[56:57]
	s_add_u32 s56, s56, s91
	s_addc_u32 s57, s57, 0
	global_load_dword v82, v26, s[56:57]
	s_add_u32 s56, s56, s91
	s_addc_u32 s57, s57, 0
	global_load_dword v83, v26, s[56:57]
	s_add_u32 s56, s56, s91
	s_addc_u32 s57, s57, 0
	global_load_dword v85, v26, s[56:57]
	s_add_u32 s56, s56, s91
	s_addc_u32 s57, s57, 0
	global_load_dword v86, v26, s[56:57]
	s_add_u32 s56, s56, s91
	s_addc_u32 s57, s57, 0
	global_load_dword v87, v26, s[56:57]
	s_add_u32 s56, s56, s91
	s_addc_u32 s57, s57, 0
	global_load_dword v88, v26, s[56:57]
	s_add_u32 s56, s56, s91
	s_addc_u32 s57, s57, 0
	global_load_dword v89, v26, s[56:57]
	s_add_u32 s56, s56, s91
	s_addc_u32 s57, s57, 0
	global_load_dword v90, v26, s[56:57]
	s_add_u32 s56, s56, s91
	s_addc_u32 s57, s57, 0
	global_load_dword v91, v26, s[56:57]
	s_add_u32 s56, s56, s91
	s_addc_u32 s57, s57, 0
	global_load_dword v92, v26, s[56:57]
	s_add_u32 s56, s56, s91
	s_addc_u32 s57, s57, 0
	global_load_dword v93, v26, s[56:57]
	s_add_u32 s56, s56, s91
	s_addc_u32 s57, s57, 0
	global_load_dword v94, v26, s[56:57]
	s_add_u32 s56, s56, s91
	s_addc_u32 s57, s57, 0
	s_waitcnt vmcnt(32) lgkmcnt(0)
	v_mul_f32_e32 v46, s36, v46
	v_mul_f32_e32 v47, s37, v47
	v_mul_f32_e32 v48, s38, v48
	v_mul_f32_e32 v49, s39, v49
	v_mul_f32_e32 v50, s40, v50
	v_mul_f32_e32 v51, s41, v51
	v_mul_f32_e32 v52, s42, v52
	v_mul_f32_e32 v53, s43, v53
	v_mul_f32_e32 v54, s44, v54
	v_mul_f32_e32 v55, s45, v55
	v_mul_f32_e32 v56, s46, v56
	v_mul_f32_e32 v57, s47, v57
	v_mul_f32_e32 v58, s48, v58
	v_mul_f32_e32 v59, s49, v59
	v_mul_f32_e32 v60, s50, v60
	v_mul_f32_e32 v61, s51, v61
	s_load_dwordx16 s[36:51], s[6:7], 0x80
	global_load_dword v95, v26, s[56:57]
	s_add_u32 s56, s56, s91
	s_addc_u32 s57, s57, 0
	global_load_dword v96, v26, s[56:57]
	s_add_u32 s56, s56, s91
	s_addc_u32 s57, s57, 0
	global_load_dword v97, v26, s[56:57]
	s_add_u32 s56, s56, s91
	s_addc_u32 s57, s57, 0
	global_load_dword v98, v26, s[56:57]
	s_add_u32 s56, s56, s91
	s_addc_u32 s57, s57, 0
	global_load_dword v99, v26, s[56:57]
	s_add_u32 s56, s56, s91
	s_addc_u32 s57, s57, 0
	global_load_dword v100, v26, s[56:57]
	s_add_u32 s56, s56, s91
	s_addc_u32 s57, s57, 0
	global_load_dword v101, v26, s[56:57]
	s_add_u32 s56, s56, s91
	s_addc_u32 s57, s57, 0
	global_load_dword v102, v26, s[56:57]
	s_add_u32 s56, s56, s91
	s_addc_u32 s57, s57, 0
	global_load_dword v103, v26, s[56:57]
	s_add_u32 s56, s56, s91
	s_addc_u32 s57, s57, 0
	global_load_dword v104, v26, s[56:57]
	s_add_u32 s56, s56, s91
	s_addc_u32 s57, s57, 0
	global_load_dword v105, v26, s[56:57]
	s_add_u32 s56, s56, s91
	s_addc_u32 s57, s57, 0
	global_load_dword v106, v26, s[56:57]
	s_add_u32 s56, s56, s91
	s_addc_u32 s57, s57, 0
	global_load_dword v107, v26, s[56:57]
	s_add_u32 s56, s56, s91
	s_addc_u32 s57, s57, 0
	global_load_dword v108, v26, s[56:57]
	s_add_u32 s56, s56, s91
	s_addc_u32 s57, s57, 0
	global_load_dword v109, v26, s[56:57]
	s_add_u32 s56, s56, s91
	s_addc_u32 s57, s57, 0
	global_load_dword v110, v26, s[56:57]
	s_add_u32 s56, s56, s91
	s_addc_u32 s57, s57, 0
	s_waitcnt vmcnt(32) lgkmcnt(0)
	v_mul_f32_e32 v62, s68, v62
	v_mul_f32_e32 v63, s69, v63
	v_mul_f32_e32 v64, s70, v64
	v_mul_f32_e32 v65, s71, v65
	v_mul_f32_e32 v66, s72, v66
	v_mul_f32_e32 v67, s73, v67
	v_mul_f32_e32 v68, s74, v68
	v_mul_f32_e32 v69, s75, v69
	v_mul_f32_e32 v70, s76, v70
	v_mul_f32_e32 v71, s77, v71
	v_mul_f32_e32 v72, s78, v72
	v_mul_f32_e32 v73, s79, v73
	v_mul_f32_e32 v74, s80, v74
	v_mul_f32_e32 v75, s81, v75
	v_mul_f32_e32 v76, s82, v76
	v_mul_f32_e32 v77, s83, v77
	s_load_dwordx16 s[68:83], s[6:7], 0xc0
	global_load_dword v111, v26, s[56:57]
	s_add_u32 s56, s56, s91
	s_addc_u32 s57, s57, 0
	global_load_dword v112, v26, s[56:57]
	s_add_u32 s56, s56, s91
	s_addc_u32 s57, s57, 0
	global_load_dword v113, v26, s[56:57]
	s_add_u32 s56, s56, s91
	s_addc_u32 s57, s57, 0
	global_load_dword v114, v26, s[56:57]
	s_add_u32 s56, s56, s91
	s_addc_u32 s57, s57, 0
	global_load_dword v115, v26, s[56:57]
	s_add_u32 s56, s56, s91
	s_addc_u32 s57, s57, 0
	global_load_dword v116, v26, s[56:57]
	s_add_u32 s56, s56, s91
	s_addc_u32 s57, s57, 0
	global_load_dword v117, v26, s[56:57]
	s_add_u32 s56, s56, s91
	s_addc_u32 s57, s57, 0
	global_load_dword v118, v26, s[56:57]
	s_add_u32 s56, s56, s91
	s_addc_u32 s57, s57, 0
	global_load_dword v119, v26, s[56:57]
	s_add_u32 s56, s56, s91
	s_addc_u32 s57, s57, 0
	global_load_dword v120, v26, s[56:57]
	s_add_u32 s56, s56, s91
	s_addc_u32 s57, s57, 0
	global_load_dword v121, v26, s[56:57]
	s_add_u32 s56, s56, s91
	s_addc_u32 s57, s57, 0
	global_load_dword v122, v26, s[56:57]
	s_add_u32 s56, s56, s91
	s_addc_u32 s57, s57, 0
	global_load_dword v123, v26, s[56:57]
	s_add_u32 s56, s56, s91
	s_addc_u32 s57, s57, 0
	global_load_dword v124, v26, s[56:57]
	s_add_u32 s56, s56, s91
	s_addc_u32 s57, s57, 0
	global_load_dword v125, v26, s[56:57]
	s_add_u32 s56, s56, s91
	s_addc_u32 s57, s57, 0
	global_load_dword v126, v26, s[56:57]
	s_add_u32 s56, s56, s91
	s_addc_u32 s57, s57, 0
	s_waitcnt vmcnt(32) lgkmcnt(0)
	v_mul_f32_e32 v78, s36, v78
	v_mul_f32_e32 v79, s37, v79
	v_mul_f32_e32 v80, s38, v80
	v_mul_f32_e32 v81, s39, v81
	v_mul_f32_e32 v82, s40, v82
	v_mul_f32_e32 v83, s41, v83
	v_mul_f32_e32 v85, s42, v85
	v_mul_f32_e32 v86, s43, v86
	v_mul_f32_e32 v87, s44, v87
	v_mul_f32_e32 v88, s45, v88
	v_mul_f32_e32 v89, s46, v89
	v_mul_f32_e32 v90, s47, v90
	v_mul_f32_e32 v91, s48, v91
	v_mul_f32_e32 v92, s49, v92
	v_mul_f32_e32 v93, s50, v93
	v_mul_f32_e32 v94, s51, v94
	s_load_dwordx16 s[36:51], s[6:7], 0x100
	global_load_dword v127, v26, s[56:57]
	s_add_u32 s56, s56, s91
	s_addc_u32 s57, s57, 0
	global_load_dword v128, v26, s[56:57]
	s_add_u32 s56, s56, s91
	s_addc_u32 s57, s57, 0
	global_load_dword v129, v26, s[56:57]
	s_add_u32 s56, s56, s91
	s_addc_u32 s57, s57, 0
	global_load_dword v130, v26, s[56:57]
	s_add_u32 s56, s56, s91
	s_addc_u32 s57, s57, 0
	global_load_dword v131, v26, s[56:57]
	s_add_u32 s56, s56, s91
	s_addc_u32 s57, s57, 0
	global_load_dword v132, v26, s[56:57]
	s_add_u32 s56, s56, s91
	s_addc_u32 s57, s57, 0
	global_load_dword v133, v26, s[56:57]
	s_add_u32 s56, s56, s91
	s_addc_u32 s57, s57, 0
	global_load_dword v134, v26, s[56:57]
	s_add_u32 s56, s56, s91
	s_addc_u32 s57, s57, 0
	global_load_dword v135, v26, s[56:57]
	s_add_u32 s56, s56, s91
	s_addc_u32 s57, s57, 0
	global_load_dword v136, v26, s[56:57]
	s_add_u32 s56, s56, s91
	s_addc_u32 s57, s57, 0
	global_load_dword v137, v26, s[56:57]
	s_add_u32 s56, s56, s91
	s_addc_u32 s57, s57, 0
	global_load_dword v140, v26, s[56:57]
	s_add_u32 s56, s56, s91
	s_addc_u32 s57, s57, 0
	global_load_dword v141, v26, s[56:57]
	s_add_u32 s56, s56, s91
	s_addc_u32 s57, s57, 0
	global_load_dword v142, v26, s[56:57]
	s_add_u32 s56, s56, s91
	s_addc_u32 s57, s57, 0
	global_load_dword v143, v26, s[56:57]
	s_add_u32 s56, s56, s91
	s_addc_u32 s57, s57, 0
	global_load_dword v144, v26, s[56:57]
	s_add_u32 s56, s56, s91
	s_addc_u32 s57, s57, 0
	s_waitcnt vmcnt(32) lgkmcnt(0)
	v_mul_f32_e32 v95, s68, v95
	v_mul_f32_e32 v96, s69, v96
	v_mul_f32_e32 v97, s70, v97
	v_mul_f32_e32 v98, s71, v98
	v_mul_f32_e32 v99, s72, v99
	v_mul_f32_e32 v100, s73, v100
	v_mul_f32_e32 v101, s74, v101
	v_mul_f32_e32 v102, s75, v102
	v_mul_f32_e32 v103, s76, v103
	v_mul_f32_e32 v104, s77, v104
	v_mul_f32_e32 v105, s78, v105
	v_mul_f32_e32 v106, s79, v106
	v_mul_f32_e32 v107, s80, v107
	v_mul_f32_e32 v108, s81, v108
	v_mul_f32_e32 v109, s82, v109
	v_mul_f32_e32 v110, s83, v110
	s_load_dwordx16 s[68:83], s[6:7], 0x140
	global_load_dword v145, v26, s[56:57]
	s_add_u32 s56, s56, s91
	s_addc_u32 s57, s57, 0
	global_load_dword v146, v26, s[56:57]
	s_add_u32 s56, s56, s91
	s_addc_u32 s57, s57, 0
	global_load_dword v147, v26, s[56:57]
	s_add_u32 s56, s56, s91
	s_addc_u32 s57, s57, 0
	global_load_dword v148, v26, s[56:57]
	s_add_u32 s56, s56, s91
	s_addc_u32 s57, s57, 0
	global_load_dword v149, v26, s[56:57]
	s_add_u32 s56, s56, s91
	s_addc_u32 s57, s57, 0
	global_load_dword v150, v26, s[56:57]
	s_add_u32 s56, s56, s91
	s_addc_u32 s57, s57, 0
	global_load_dword v151, v26, s[56:57]
	s_add_u32 s56, s56, s91
	s_addc_u32 s57, s57, 0
	global_load_dword v152, v26, s[56:57]
	s_add_u32 s56, s56, s91
	s_addc_u32 s57, s57, 0
	global_load_dword v153, v26, s[56:57]
	s_add_u32 s56, s56, s91
	s_addc_u32 s57, s57, 0
	global_load_dword v154, v26, s[56:57]
	s_add_u32 s56, s56, s91
	s_addc_u32 s57, s57, 0
	global_load_dword v156, v26, s[56:57]
	s_add_u32 s56, s56, s91
	s_addc_u32 s57, s57, 0
	global_load_dword v157, v26, s[56:57]
	s_add_u32 s56, s56, s91
	s_addc_u32 s57, s57, 0
	global_load_dword v158, v26, s[56:57]
	s_add_u32 s56, s56, s91
	s_addc_u32 s57, s57, 0
	global_load_dword v159, v26, s[56:57]
	s_add_u32 s56, s56, s91
	s_addc_u32 s57, s57, 0
	global_load_dword v160, v26, s[56:57]
	s_add_u32 s56, s56, s91
	s_addc_u32 s57, s57, 0
	global_load_dword v161, v26, s[56:57]
	s_add_u32 s56, s56, s91
	s_addc_u32 s57, s57, 0
	s_waitcnt vmcnt(32) lgkmcnt(0)
	v_mul_f32_e32 v111, s36, v111
	v_mul_f32_e32 v112, s37, v112
	v_mul_f32_e32 v113, s38, v113
	v_mul_f32_e32 v114, s39, v114
	v_mul_f32_e32 v115, s40, v115
	v_mul_f32_e32 v116, s41, v116
	v_mul_f32_e32 v117, s42, v117
	v_mul_f32_e32 v118, s43, v118
	v_mul_f32_e32 v119, s44, v119
	v_mul_f32_e32 v120, s45, v120
	v_mul_f32_e32 v121, s46, v121
	v_mul_f32_e32 v122, s47, v122
	v_mul_f32_e32 v123, s48, v123
	v_mul_f32_e32 v124, s49, v124
	v_mul_f32_e32 v125, s50, v125
	v_mul_f32_e32 v126, s51, v126
	s_load_dwordx16 s[36:51], s[6:7], 0x180
	global_load_dword v162, v26, s[56:57]
	s_add_u32 s56, s56, s91
	s_addc_u32 s57, s57, 0
	global_load_dword v163, v26, s[56:57]
	s_add_u32 s56, s56, s91
	s_addc_u32 s57, s57, 0
	global_load_dword v164, v26, s[56:57]
	s_add_u32 s56, s56, s91
	s_addc_u32 s57, s57, 0
	global_load_dword v165, v26, s[56:57]
	s_add_u32 s56, s56, s91
	s_addc_u32 s57, s57, 0
	global_load_dword v166, v26, s[56:57]
	s_add_u32 s56, s56, s91
	s_addc_u32 s57, s57, 0
	global_load_dword v167, v26, s[56:57]
	s_add_u32 s56, s56, s91
	s_addc_u32 s57, s57, 0
	global_load_dword v168, v26, s[56:57]
	s_add_u32 s56, s56, s91
	s_addc_u32 s57, s57, 0
	global_load_dword v169, v26, s[56:57]
	s_add_u32 s56, s56, s91
	s_addc_u32 s57, s57, 0
	global_load_dword v170, v26, s[56:57]
	s_add_u32 s56, s56, s91
	s_addc_u32 s57, s57, 0
	global_load_dword v171, v26, s[56:57]
	s_add_u32 s56, s56, s91
	s_addc_u32 s57, s57, 0
	global_load_dword v172, v26, s[56:57]
	s_add_u32 s56, s56, s91
	s_addc_u32 s57, s57, 0
	global_load_dword v173, v26, s[56:57]
	s_add_u32 s56, s56, s91
	s_addc_u32 s57, s57, 0
	global_load_dword v174, v26, s[56:57]
	s_add_u32 s56, s56, s91
	s_addc_u32 s57, s57, 0
	global_load_dword v175, v26, s[56:57]
	s_add_u32 s56, s56, s91
	s_addc_u32 s57, s57, 0
	global_load_dword v176, v26, s[56:57]
	s_add_u32 s56, s56, s91
	s_addc_u32 s57, s57, 0
	global_load_dword v177, v26, s[56:57]
	s_waitcnt vmcnt(32) lgkmcnt(0)
	v_mul_f32_e32 v127, s68, v127
	v_mul_f32_e32 v128, s69, v128
	v_mul_f32_e32 v129, s70, v129
	v_mul_f32_e32 v130, s71, v130
	v_mul_f32_e32 v131, s72, v131
	v_mul_f32_e32 v132, s73, v132
	v_mul_f32_e32 v133, s74, v133
	v_mul_f32_e32 v134, s75, v134
	v_mul_f32_e32 v135, s76, v135
	v_mul_f32_e32 v136, s77, v136
	v_mul_f32_e32 v137, s78, v137
	v_mul_f32_e32 v140, s79, v140
	v_mul_f32_e32 v141, s80, v141
	v_mul_f32_e32 v142, s81, v142
	v_mul_f32_e32 v143, s82, v143
	v_mul_f32_e32 v144, s83, v144
	s_load_dwordx16 s[68:83], s[6:7], 0x1c0
	s_waitcnt vmcnt(16) lgkmcnt(0)
	v_mul_f32_e32 v145, s36, v145
	v_mul_f32_e32 v146, s37, v146
	v_mul_f32_e32 v147, s38, v147
	v_mul_f32_e32 v148, s39, v148
	v_mul_f32_e32 v149, s40, v149
	v_mul_f32_e32 v150, s41, v150
	v_mul_f32_e32 v151, s42, v151
	v_mul_f32_e32 v152, s43, v152
	v_mul_f32_e32 v153, s44, v153
	v_mul_f32_e32 v154, s45, v154
	v_mul_f32_e32 v156, s46, v156
	v_mul_f32_e32 v157, s47, v157
	v_mul_f32_e32 v158, s48, v158
	v_mul_f32_e32 v159, s49, v159
	v_mul_f32_e32 v160, s50, v160
	v_mul_f32_e32 v161, s51, v161
	s_waitcnt vmcnt(0)
	v_mul_f32_e32 v162, s68, v162
	v_mul_f32_e32 v163, s69, v163
	v_mul_f32_e32 v164, s70, v164
	v_mul_f32_e32 v165, s71, v165
	v_mul_f32_e32 v166, s72, v166
	v_mul_f32_e32 v167, s73, v167
	v_mul_f32_e32 v168, s74, v168
	v_mul_f32_e32 v169, s75, v169
	v_mul_f32_e32 v170, s76, v170
	v_mul_f32_e32 v171, s77, v171
	v_mul_f32_e32 v172, s78, v172
	v_mul_f32_e32 v173, s79, v173
	v_mul_f32_e32 v174, s80, v174
	v_mul_f32_e32 v175, s81, v175
	v_mul_f32_e32 v176, s82, v176
	v_mul_f32_e32 v177, s83, v177
	s_load_dwordx16 s[36:51], s[52:53], 0x0
	s_mov_b32 s30, 0
.Lwf_fold_loop:
	v_mov_b32_e32 v0, 0
	s_waitcnt lgkmcnt(0)
	s_load_dwordx16 s[68:83], s[52:53], 0x40
	v_fmac_f32_e32 v0, s36, v46
	v_fmac_f32_e32 v0, s37, v47
	v_fmac_f32_e32 v0, s38, v48
	v_fmac_f32_e32 v0, s39, v49
	v_fmac_f32_e32 v0, s40, v50
	v_fmac_f32_e32 v0, s41, v51
	v_fmac_f32_e32 v0, s42, v52
	v_fmac_f32_e32 v0, s43, v53
	v_fmac_f32_e32 v0, s44, v54
	v_fmac_f32_e32 v0, s45, v55
	v_fmac_f32_e32 v0, s46, v56
	v_fmac_f32_e32 v0, s47, v57
	v_fmac_f32_e32 v0, s48, v58
	v_fmac_f32_e32 v0, s49, v59
	v_fmac_f32_e32 v0, s50, v60
	v_fmac_f32_e32 v0, s51, v61
	s_waitcnt lgkmcnt(0)
	s_load_dwordx16 s[36:51], s[52:53], 0x80
	v_fmac_f32_e32 v0, s68, v62
	v_fmac_f32_e32 v0, s69, v63
	v_fmac_f32_e32 v0, s70, v64
	v_fmac_f32_e32 v0, s71, v65
	v_fmac_f32_e32 v0, s72, v66
	v_fmac_f32_e32 v0, s73, v67
	v_fmac_f32_e32 v0, s74, v68
	v_fmac_f32_e32 v0, s75, v69
	v_fmac_f32_e32 v0, s76, v70
	v_fmac_f32_e32 v0, s77, v71
	v_fmac_f32_e32 v0, s78, v72
	v_fmac_f32_e32 v0, s79, v73
	v_fmac_f32_e32 v0, s80, v74
	v_fmac_f32_e32 v0, s81, v75
	v_fmac_f32_e32 v0, s82, v76
	v_fmac_f32_e32 v0, s83, v77
	s_waitcnt lgkmcnt(0)
	s_load_dwordx16 s[68:83], s[52:53], 0xc0
	v_fmac_f32_e32 v0, s36, v78
	v_fmac_f32_e32 v0, s37, v79
	v_fmac_f32_e32 v0, s38, v80
	v_fmac_f32_e32 v0, s39, v81
	v_fmac_f32_e32 v0, s40, v82
	v_fmac_f32_e32 v0, s41, v83
	v_fmac_f32_e32 v0, s42, v85
	v_fmac_f32_e32 v0, s43, v86
	v_fmac_f32_e32 v0, s44, v87
	v_fmac_f32_e32 v0, s45, v88
	v_fmac_f32_e32 v0, s46, v89
	v_fmac_f32_e32 v0, s47, v90
	v_fmac_f32_e32 v0, s48, v91
	v_fmac_f32_e32 v0, s49, v92
	v_fmac_f32_e32 v0, s50, v93
	v_fmac_f32_e32 v0, s51, v94
	s_waitcnt lgkmcnt(0)
	s_load_dwordx16 s[36:51], s[52:53], 0x100
	v_fmac_f32_e32 v0, s68, v95
	v_fmac_f32_e32 v0, s69, v96
	v_fmac_f32_e32 v0, s70, v97
	v_fmac_f32_e32 v0, s71, v98
	v_fmac_f32_e32 v0, s72, v99
	v_fmac_f32_e32 v0, s73, v100
	v_fmac_f32_e32 v0, s74, v101
	v_fmac_f32_e32 v0, s75, v102
	v_fmac_f32_e32 v0, s76, v103
	v_fmac_f32_e32 v0, s77, v104
	v_fmac_f32_e32 v0, s78, v105
	v_fmac_f32_e32 v0, s79, v106
	v_fmac_f32_e32 v0, s80, v107
	v_fmac_f32_e32 v0, s81, v108
	v_fmac_f32_e32 v0, s82, v109
	v_fmac_f32_e32 v0, s83, v110
	s_waitcnt lgkmcnt(0)
	s_load_dwordx16 s[68:83], s[52:53], 0x140
	v_fmac_f32_e32 v0, s36, v111
	v_fmac_f32_e32 v0, s37, v112
	v_fmac_f32_e32 v0, s38, v113
	v_fmac_f32_e32 v0, s39, v114
	v_fmac_f32_e32 v0, s40, v115
	v_fmac_f32_e32 v0, s41, v116
	v_fmac_f32_e32 v0, s42, v117
	v_fmac_f32_e32 v0, s43, v118
	v_fmac_f32_e32 v0, s44, v119
	v_fmac_f32_e32 v0, s45, v120
	v_fmac_f32_e32 v0, s46, v121
	v_fmac_f32_e32 v0, s47, v122
	v_fmac_f32_e32 v0, s48, v123
	v_fmac_f32_e32 v0, s49, v124
	v_fmac_f32_e32 v0, s50, v125
	v_fmac_f32_e32 v0, s51, v126
	s_waitcnt lgkmcnt(0)
	s_load_dwordx16 s[36:51], s[52:53], 0x180
	v_fmac_f32_e32 v0, s68, v127
	v_fmac_f32_e32 v0, s69, v128
	v_fmac_f32_e32 v0, s70, v129
	v_fmac_f32_e32 v0, s71, v130
	v_fmac_f32_e32 v0, s72, v131
	v_fmac_f32_e32 v0, s73, v132
	v_fmac_f32_e32 v0, s74, v133
	v_fmac_f32_e32 v0, s75, v134
	v_fmac_f32_e32 v0, s76, v135
	v_fmac_f32_e32 v0, s77, v136
	v_fmac_f32_e32 v0, s78, v137
	v_fmac_f32_e32 v0, s79, v140
	v_fmac_f32_e32 v0, s80, v141
	v_fmac_f32_e32 v0, s81, v142
	v_fmac_f32_e32 v0, s82, v143
	v_fmac_f32_e32 v0, s83, v144
	s_waitcnt lgkmcnt(0)
	s_load_dwordx16 s[68:83], s[52:53], 0x1c0
	v_fmac_f32_e32 v0, s36, v145
	v_fmac_f32_e32 v0, s37, v146
	v_fmac_f32_e32 v0, s38, v147
	v_fmac_f32_e32 v0, s39, v148
	v_fmac_f32_e32 v0, s40, v149
	v_fmac_f32_e32 v0, s41, v150
	v_fmac_f32_e32 v0, s42, v151
	v_fmac_f32_e32 v0, s43, v152
	v_fmac_f32_e32 v0, s44, v153
	v_fmac_f32_e32 v0, s45, v154
	v_fmac_f32_e32 v0, s46, v156
	v_fmac_f32_e32 v0, s47, v157
	v_fmac_f32_e32 v0, s48, v158
	v_fmac_f32_e32 v0, s49, v159
	v_fmac_f32_e32 v0, s50, v160
	v_fmac_f32_e32 v0, s51, v161
	s_waitcnt lgkmcnt(0)
	s_load_dwordx16 s[36:51], s[52:53], 0x200
	v_fmac_f32_e32 v0, s68, v162
	v_fmac_f32_e32 v0, s69, v163
	v_fmac_f32_e32 v0, s70, v164
	v_fmac_f32_e32 v0, s71, v165
	v_fmac_f32_e32 v0, s72, v166
	v_fmac_f32_e32 v0, s73, v167
	v_fmac_f32_e32 v0, s74, v168
	v_fmac_f32_e32 v0, s75, v169
	v_fmac_f32_e32 v0, s76, v170
	v_fmac_f32_e32 v0, s77, v171
	v_fmac_f32_e32 v0, s78, v172
	v_fmac_f32_e32 v0, s79, v173
	v_fmac_f32_e32 v0, s80, v174
	v_fmac_f32_e32 v0, s81, v175
	v_fmac_f32_e32 v0, s82, v176
	v_fmac_f32_e32 v0, s83, v177
	v_mov_b32_e32 v1, 0
	s_waitcnt lgkmcnt(0)
	s_load_dwordx16 s[68:83], s[52:53], 0x240
	v_fmac_f32_e32 v1, s36, v46
	v_fmac_f32_e32 v1, s37, v47
	v_fmac_f32_e32 v1, s38, v48
	v_fmac_f32_e32 v1, s39, v49
	v_fmac_f32_e32 v1, s40, v50
	v_fmac_f32_e32 v1, s41, v51
	v_fmac_f32_e32 v1, s42, v52
	v_fmac_f32_e32 v1, s43, v53
	v_fmac_f32_e32 v1, s44, v54
	v_fmac_f32_e32 v1, s45, v55
	v_fmac_f32_e32 v1, s46, v56
	v_fmac_f32_e32 v1, s47, v57
	v_fmac_f32_e32 v1, s48, v58
	v_fmac_f32_e32 v1, s49, v59
	v_fmac_f32_e32 v1, s50, v60
	v_fmac_f32_e32 v1, s51, v61
	s_waitcnt lgkmcnt(0)
	s_load_dwordx16 s[36:51], s[52:53], 0x280
	v_fmac_f32_e32 v1, s68, v62
	v_fmac_f32_e32 v1, s69, v63
	v_fmac_f32_e32 v1, s70, v64
	v_fmac_f32_e32 v1, s71, v65
	v_fmac_f32_e32 v1, s72, v66
	v_fmac_f32_e32 v1, s73, v67
	v_fmac_f32_e32 v1, s74, v68
	v_fmac_f32_e32 v1, s75, v69
	v_fmac_f32_e32 v1, s76, v70
	v_fmac_f32_e32 v1, s77, v71
	v_fmac_f32_e32 v1, s78, v72
	v_fmac_f32_e32 v1, s79, v73
	v_fmac_f32_e32 v1, s80, v74
	v_fmac_f32_e32 v1, s81, v75
	v_fmac_f32_e32 v1, s82, v76
	v_fmac_f32_e32 v1, s83, v77
	s_waitcnt lgkmcnt(0)
	s_load_dwordx16 s[68:83], s[52:53], 0x2c0
	v_fmac_f32_e32 v1, s36, v78
	v_fmac_f32_e32 v1, s37, v79
	v_fmac_f32_e32 v1, s38, v80
	v_fmac_f32_e32 v1, s39, v81
	v_fmac_f32_e32 v1, s40, v82
	v_fmac_f32_e32 v1, s41, v83
	v_fmac_f32_e32 v1, s42, v85
	v_fmac_f32_e32 v1, s43, v86
	v_fmac_f32_e32 v1, s44, v87
	v_fmac_f32_e32 v1, s45, v88
	v_fmac_f32_e32 v1, s46, v89
	v_fmac_f32_e32 v1, s47, v90
	v_fmac_f32_e32 v1, s48, v91
	v_fmac_f32_e32 v1, s49, v92
	v_fmac_f32_e32 v1, s50, v93
	v_fmac_f32_e32 v1, s51, v94
	s_waitcnt lgkmcnt(0)
	s_load_dwordx16 s[36:51], s[52:53], 0x300
	v_fmac_f32_e32 v1, s68, v95
	v_fmac_f32_e32 v1, s69, v96
	v_fmac_f32_e32 v1, s70, v97
	v_fmac_f32_e32 v1, s71, v98
	v_fmac_f32_e32 v1, s72, v99
	v_fmac_f32_e32 v1, s73, v100
	v_fmac_f32_e32 v1, s74, v101
	v_fmac_f32_e32 v1, s75, v102
	v_fmac_f32_e32 v1, s76, v103
	v_fmac_f32_e32 v1, s77, v104
	v_fmac_f32_e32 v1, s78, v105
	v_fmac_f32_e32 v1, s79, v106
	v_fmac_f32_e32 v1, s80, v107
	v_fmac_f32_e32 v1, s81, v108
	v_fmac_f32_e32 v1, s82, v109
	v_fmac_f32_e32 v1, s83, v110
	s_waitcnt lgkmcnt(0)
	s_load_dwordx16 s[68:83], s[52:53], 0x340
	v_fmac_f32_e32 v1, s36, v111
	v_fmac_f32_e32 v1, s37, v112
	v_fmac_f32_e32 v1, s38, v113
	v_fmac_f32_e32 v1, s39, v114
	v_fmac_f32_e32 v1, s40, v115
	v_fmac_f32_e32 v1, s41, v116
	v_fmac_f32_e32 v1, s42, v117
	v_fmac_f32_e32 v1, s43, v118
	v_fmac_f32_e32 v1, s44, v119
	v_fmac_f32_e32 v1, s45, v120
	v_fmac_f32_e32 v1, s46, v121
	v_fmac_f32_e32 v1, s47, v122
	v_fmac_f32_e32 v1, s48, v123
	v_fmac_f32_e32 v1, s49, v124
	v_fmac_f32_e32 v1, s50, v125
	v_fmac_f32_e32 v1, s51, v126
	s_waitcnt lgkmcnt(0)
	s_load_dwordx16 s[36:51], s[52:53], 0x380
	v_fmac_f32_e32 v1, s68, v127
	v_fmac_f32_e32 v1, s69, v128
	v_fmac_f32_e32 v1, s70, v129
	v_fmac_f32_e32 v1, s71, v130
	v_fmac_f32_e32 v1, s72, v131
	v_fmac_f32_e32 v1, s73, v132
	v_fmac_f32_e32 v1, s74, v133
	v_fmac_f32_e32 v1, s75, v134
	v_fmac_f32_e32 v1, s76, v135
	v_fmac_f32_e32 v1, s77, v136
	v_fmac_f32_e32 v1, s78, v137
	v_fmac_f32_e32 v1, s79, v140
	v_fmac_f32_e32 v1, s80, v141
	v_fmac_f32_e32 v1, s81, v142
	v_fmac_f32_e32 v1, s82, v143
	v_fmac_f32_e32 v1, s83, v144
	s_waitcnt lgkmcnt(0)
	s_load_dwordx16 s[68:83], s[52:53], 0x3c0
	v_fmac_f32_e32 v1, s36, v145
	v_fmac_f32_e32 v1, s37, v146
	v_fmac_f32_e32 v1, s38, v147
	v_fmac_f32_e32 v1, s39, v148
	v_fmac_f32_e32 v1, s40, v149
	v_fmac_f32_e32 v1, s41, v150
	v_fmac_f32_e32 v1, s42, v151
	v_fmac_f32_e32 v1, s43, v152
	v_fmac_f32_e32 v1, s44, v153
	v_fmac_f32_e32 v1, s45, v154
	v_fmac_f32_e32 v1, s46, v156
	v_fmac_f32_e32 v1, s47, v157
	v_fmac_f32_e32 v1, s48, v158
	v_fmac_f32_e32 v1, s49, v159
	v_fmac_f32_e32 v1, s50, v160
	v_fmac_f32_e32 v1, s51, v161
	s_waitcnt lgkmcnt(0)
	s_cmp_eq_u32 s30, 7
	s_cbranch_scc1 .Lwf_fold_nopf
	s_load_dwordx16 s[36:51], s[52:53], 0x400
.Lwf_fold_nopf:
	v_fmac_f32_e32 v1, s68, v162
	v_fmac_f32_e32 v1, s69, v163
	v_fmac_f32_e32 v1, s70, v164
	v_fmac_f32_e32 v1, s71, v165
	v_fmac_f32_e32 v1, s72, v166
	v_fmac_f32_e32 v1, s73, v167
	v_fmac_f32_e32 v1, s74, v168
	v_fmac_f32_e32 v1, s75, v169
	v_fmac_f32_e32 v1, s76, v170
	v_fmac_f32_e32 v1, s77, v171
	v_fmac_f32_e32 v1, s78, v172
	v_fmac_f32_e32 v1, s79, v173
	v_fmac_f32_e32 v1, s80, v174
	v_fmac_f32_e32 v1, s81, v175
	v_fmac_f32_e32 v1, s82, v176
	v_fmac_f32_e32 v1, s83, v177
	v_cvt_pk_bf16_f32 v38, v0, v1
	v_mov_b32_e32 v30, v31
	v_mov_b32_e32 v31, v32
	v_mov_b32_e32 v32, v33
	v_mov_b32_e32 v33, v34
	v_mov_b32_e32 v34, v35
	v_mov_b32_e32 v35, v36
	v_mov_b32_e32 v36, v37
	v_mov_b32_e32 v37, v38
	s_add_u32 s52, s52, 0x400
	s_addc_u32 s53, s53, 0
	s_add_i32 s30, s30, 1
	s_cmp_lt_u32 s30, 8
	s_cbranch_scc1 .Lwf_fold_loop
	global_store_dwordx4 v27, v[30:33], s[54:55]
	global_store_dwordx4 v27, v[34:37], s[54:55] offset:16
	s_movk_i32 s68, 0x2000
	s_movk_i32 s69, 0x60
	s_mov_b64 s[36:37], 0x1200
	s_mov_b64 s[38:39], 0x1400
	s_mov_b64 s[40:41], 0x1600
	s_mov_b64 s[42:43], 0x1800
	s_mov_b64 s[44:45], 0x1a00
	s_mov_b64 s[46:47], 0x1c00
	s_mov_b64 s[48:49], 0x1e00
	s_movk_i32 s70, 0x2400
	s_movk_i32 s71, 0x400
	s_movk_i32 s72, 0xfc00
	s_mov_b32 s73, 0xbfb8aa3b
	s_mov_b32 s74, 0x42ce8ed0
	s_mov_b32 s75, 0xc2b17218
	s_movk_i32 s76, 0xfbff
	s_movk_i32 s77, 0x21ff
	s_movk_i32 s78, 0x6000
	s_mov_b32 s79, 0x18000
	s_mov_b32 s80, 0x30000
	s_mov_b32 s81, 0x48000
	s_mov_b32 s82, 0x60000
	s_mov_b32 s83, 0x78000
	s_load_dword s6, s[0:1], 0x4c8
	s_waitcnt lgkmcnt(0)
	s_add_i32 s89, s89, s6
	s_cmp_ge_i32 s89, s62
	s_cbranch_scc1 .LBB0_113
	s_branch .LBB0_24

.LBB0_24:
	s_cmpk_lt_i32 s89, 0x180
	s_cbranch_scc1 .Lwf_generic
	s_cmpk_ge_i32 s89, 0x1680
	s_cbranch_scc1 .Lwf_generic
	s_cmpk_lg_u32 s61, 0x16e0
	s_cbranch_scc1 .Lwf_generic
	s_cmpk_ge_i32 s89, 0x280
	s_cbranch_scc1 .Lwf_plain
	s_and_b32 s6, s89, 7
	s_cmp_lt_u32 s6, 4
	s_cbranch_scc1 .Lwf_fold
	s_branch .Lwf_generic
.Lwf_plain:
	v_and_b32_e32 v29, 63, v155
	v_lshrrev_b32_e32 v24, 6, v155
	v_lshlrev_b32_e32 v26, 2, v29
	v_lshlrev_b32_e32 v29, 1, v29
	v_readfirstlane_b32 s58, v24
	s_load_dword s6, s[0:1], 0x4c8
	s_waitcnt lgkmcnt(0)
	s_lshl_b32 s58, s58, 4
	s_add_i32 s7, s89, 0xfffffe80
	s_mov_b32 s30, 2
	s_cmpk_ge_i32 s7, 0x300
	s_cselect_b32 s30, 3, s30
	s_cmpk_ge_i32 s7, 0x500
	s_cselect_b32 s30, 4, s30
	s_cmpk_ge_i32 s7, 0x700
	s_cselect_b32 s30, 5, s30
	s_cmpk_ge_i32 s7, 0x900
	s_cselect_b32 s30, 6, s30
	s_cmpk_ge_i32 s7, 0xb00
	s_cselect_b32 s30, 7, s30
	s_cmpk_ge_i32 s7, 0xd00
	s_cselect_b32 s30, 8, s30
	s_cmpk_ge_i32 s7, 0xf00
	s_cselect_b32 s30, 9, s30
	s_cmpk_ge_i32 s7, 0x1100
	s_cselect_b32 s30, 10, s30
	s_cmpk_ge_i32 s7, 0x1280
	s_cselect_b32 s30, 11, s30
	s_cmpk_ge_i32 s7, 0x1400
	s_cselect_b32 s30, 12, s30
	s_cmpk_ge_i32 s7, 0x1480
	s_cselect_b32 s30, 13, s30
	s_mul_i32 s59, s30, 48
	s_add_u32 s10, s0, s59
	s_addc_u32 s11, s1, 0
	s_load_dwordx2 s[50:51], s[10:11], 0x100
	s_load_dwordx2 s[52:53], s[10:11], 0x110
	s_load_dwordx2 s[90:91], s[10:11], 0x118
	s_load_dword s30, s[10:11], 0x128
	s_load_dwordx2 vcc, s[0:1], 0xf8
	s_waitcnt lgkmcnt(0)
	s_sub_i32 s7, s7, s30
	s_lshr_b32 s59, s90, 7
	s_add_i32 s10, s59, -1
	s_and_b32 s10, s7, s10
	s_ff1_i32_b32 s59, s59
	s_lshr_b32 s7, s7, s59
	s_lshl_b32 s10, s10, 7
	s_add_i32 s10, s10, s58
	s_lshl_b32 s11, s7, 6
	s_mul_i32 s59, s10, s91
	s_add_i32 s59, s59, s11
	s_lshl_b32 s59, s59, 2
	s_add_u32 s50, s50, s59
	s_addc_u32 s51, s51, 0
	s_mul_i32 s59, s11, s90
	s_add_i32 s59, s59, s10
	s_lshl_b32 s59, s59, 1
	s_add_u32 s52, s52, s59
	s_addc_u32 s53, s53, 0
	s_add_u32 s52, s52, vcc_lo
	s_addc_u32 s53, s53, vcc_hi
	v_mul_u32_u24_e32 v27, s90, v29
	s_lshl_b32 s91, s91, 2
	global_load_dword v0, v26, s[50:51] nt
	s_add_u32 s50, s50, s91
	s_addc_u32 s51, s51, 0
	global_load_dword v1, v26, s[50:51] nt
	s_add_u32 s50, s50, s91
	s_addc_u32 s51, s51, 0
	global_load_dword v2, v26, s[50:51] nt
	s_add_u32 s50, s50, s91
	s_addc_u32 s51, s51, 0
	global_load_dword v3, v26, s[50:51] nt
	s_add_u32 s50, s50, s91
	s_addc_u32 s51, s51, 0
	global_load_dword v4, v26, s[50:51] nt
	s_add_u32 s50, s50, s91
	s_addc_u32 s51, s51, 0
	global_load_dword v5, v26, s[50:51] nt
	s_add_u32 s50, s50, s91
	s_addc_u32 s51, s51, 0
	global_load_dword v6, v26, s[50:51] nt
	s_add_u32 s50, s50, s91
	s_addc_u32 s51, s51, 0
	global_load_dword v7, v26, s[50:51] nt
	s_add_u32 s50, s50, s91
	s_addc_u32 s51, s51, 0
	global_load_dword v8, v26, s[50:51] nt
	s_add_u32 s50, s50, s91
	s_addc_u32 s51, s51, 0
	global_load_dword v9, v26, s[50:51] nt
	s_add_u32 s50, s50, s91
	s_addc_u32 s51, s51, 0
	global_load_dword v10, v26, s[50:51] nt
	s_add_u32 s50, s50, s91
	s_addc_u32 s51, s51, 0
	global_load_dword v11, v26, s[50:51] nt
	s_add_u32 s50, s50, s91
	s_addc_u32 s51, s51, 0
	global_load_dword v12, v26, s[50:51] nt
	s_add_u32 s50, s50, s91
	s_addc_u32 s51, s51, 0
	global_load_dword v13, v26, s[50:51] nt
	s_add_u32 s50, s50, s91
	s_addc_u32 s51, s51, 0
	global_load_dword v14, v26, s[50:51] nt
	s_add_u32 s50, s50, s91
	s_addc_u32 s51, s51, 0
	global_load_dword v15, v26, s[50:51] nt
	s_add_i32 s89, s89, s6
	s_cmpk_ge_i32 s89, 0x1680
	s_cbranch_scc1 .Lwf_pdrain1
	s_add_i32 s7, s89, 0xfffffe80
	s_mov_b32 s30, 2
	s_cmpk_ge_i32 s7, 0x300
	s_cselect_b32 s30, 3, s30
	s_cmpk_ge_i32 s7, 0x500
	s_cselect_b32 s30, 4, s30
	s_cmpk_ge_i32 s7, 0x700
	s_cselect_b32 s30, 5, s30
	s_cmpk_ge_i32 s7, 0x900
	s_cselect_b32 s30, 6, s30
	s_cmpk_ge_i32 s7, 0xb00
	s_cselect_b32 s30, 7, s30
	s_cmpk_ge_i32 s7, 0xd00
	s_cselect_b32 s30, 8, s30
	s_cmpk_ge_i32 s7, 0xf00
	s_cselect_b32 s30, 9, s30
	s_cmpk_ge_i32 s7, 0x1100
	s_cselect_b32 s30, 10, s30
	s_cmpk_ge_i32 s7, 0x1280
	s_cselect_b32 s30, 11, s30
	s_cmpk_ge_i32 s7, 0x1400
	s_cselect_b32 s30, 12, s30
	s_cmpk_ge_i32 s7, 0x1480
	s_cselect_b32 s30, 13, s30
	s_mul_i32 s59, s30, 48
	s_add_u32 s10, s0, s59
	s_addc_u32 s11, s1, 0
	s_load_dwordx2 s[50:51], s[10:11], 0x100
	s_load_dwordx2 s[54:55], s[10:11], 0x110
	s_load_dwordx2 s[90:91], s[10:11], 0x118
	s_load_dword s30, s[10:11], 0x128
	s_load_dwordx2 vcc, s[0:1], 0xf8
	s_waitcnt lgkmcnt(0)
	s_sub_i32 s7, s7, s30
	s_lshr_b32 s59, s90, 7
	s_add_i32 s10, s59, -1
	s_and_b32 s10, s7, s10
	s_ff1_i32_b32 s59, s59
	s_lshr_b32 s7, s7, s59
	s_lshl_b32 s10, s10, 7
	s_add_i32 s10, s10, s58
	s_lshl_b32 s11, s7, 6
	s_mul_i32 s59, s10, s91
	s_add_i32 s59, s59, s11
	s_lshl_b32 s59, s59, 2
	s_add_u32 s50, s50, s59
	s_addc_u32 s51, s51, 0
	s_mul_i32 s59, s11, s90
	s_add_i32 s59, s59, s10
	s_lshl_b32 s59, s59, 1
	s_add_u32 s54, s54, s59
	s_addc_u32 s55, s55, 0
	s_add_u32 s54, s54, vcc_lo
	s_addc_u32 s55, s55, vcc_hi
	v_mul_u32_u24_e32 v28, s90, v29
	s_lshl_b32 s91, s91, 2
	global_load_dword v30, v26, s[50:51] nt
	s_add_u32 s50, s50, s91
	s_addc_u32 s51, s51, 0
	global_load_dword v31, v26, s[50:51] nt
	s_add_u32 s50, s50, s91
	s_addc_u32 s51, s51, 0
	global_load_dword v32, v26, s[50:51] nt
	s_add_u32 s50, s50, s91
	s_addc_u32 s51, s51, 0
	global_load_dword v33, v26, s[50:51] nt
	s_add_u32 s50, s50, s91
	s_addc_u32 s51, s51, 0
	global_load_dword v34, v26, s[50:51] nt
	s_add_u32 s50, s50, s91
	s_addc_u32 s51, s51, 0
	global_load_dword v35, v26, s[50:51] nt
	s_add_u32 s50, s50, s91
	s_addc_u32 s51, s51, 0
	global_load_dword v36, v26, s[50:51] nt
	s_add_u32 s50, s50, s91
	s_addc_u32 s51, s51, 0
	global_load_dword v37, v26, s[50:51] nt
	s_add_u32 s50, s50, s91
	s_addc_u32 s51, s51, 0
	global_load_dword v38, v26, s[50:51] nt
	s_add_u32 s50, s50, s91
	s_addc_u32 s51, s51, 0
	global_load_dword v39, v26, s[50:51] nt
	s_add_u32 s50, s50, s91
	s_addc_u32 s51, s51, 0
	global_load_dword v40, v26, s[50:51] nt
	s_add_u32 s50, s50, s91
	s_addc_u32 s51, s51, 0
	global_load_dword v41, v26, s[50:51] nt
	s_add_u32 s50, s50, s91
	s_addc_u32 s51, s51, 0
	global_load_dword v42, v26, s[50:51] nt
	s_add_u32 s50, s50, s91
	s_addc_u32 s51, s51, 0
	global_load_dword v43, v26, s[50:51] nt
	s_add_u32 s50, s50, s91
	s_addc_u32 s51, s51, 0
	global_load_dword v44, v26, s[50:51] nt
	s_add_u32 s50, s50, s91
	s_addc_u32 s51, s51, 0
	global_load_dword v45, v26, s[50:51] nt
	s_add_i32 s89, s89, s6
	s_cmpk_ge_i32 s89, 0x1680
	s_cbranch_scc1 .Lwf_pdrain2
	s_add_i32 s7, s89, 0xfffffe80
	s_mov_b32 s30, 2
	s_cmpk_ge_i32 s7, 0x300
	s_cselect_b32 s30, 3, s30
	s_cmpk_ge_i32 s7, 0x500
	s_cselect_b32 s30, 4, s30
	s_cmpk_ge_i32 s7, 0x700
	s_cselect_b32 s30, 5, s30
	s_cmpk_ge_i32 s7, 0x900
	s_cselect_b32 s30, 6, s30
	s_cmpk_ge_i32 s7, 0xb00
	s_cselect_b32 s30, 7, s30
	s_cmpk_ge_i32 s7, 0xd00
	s_cselect_b32 s30, 8, s30
	s_cmpk_ge_i32 s7, 0xf00
	s_cselect_b32 s30, 9, s30
	s_cmpk_ge_i32 s7, 0x1100
	s_cselect_b32 s30, 10, s30
	s_cmpk_ge_i32 s7, 0x1280
	s_cselect_b32 s30, 11, s30
	s_cmpk_ge_i32 s7, 0x1400
	s_cselect_b32 s30, 12, s30
	s_cmpk_ge_i32 s7, 0x1480
	s_cselect_b32 s30, 13, s30
	s_mul_i32 s59, s30, 48
	s_add_u32 s10, s0, s59
	s_addc_u32 s11, s1, 0
	s_load_dwordx2 s[50:51], s[10:11], 0x100
	s_load_dwordx2 s[56:57], s[10:11], 0x110
	s_load_dwordx2 s[90:91], s[10:11], 0x118
	s_load_dword s30, s[10:11], 0x128
	s_load_dwordx2 vcc, s[0:1], 0xf8
	s_waitcnt lgkmcnt(0)
	s_sub_i32 s7, s7, s30
	s_lshr_b32 s59, s90, 7
	s_add_i32 s10, s59, -1
	s_and_b32 s10, s7, s10
	s_ff1_i32_b32 s59, s59
	s_lshr_b32 s7, s7, s59
	s_lshl_b32 s10, s10, 7
	s_add_i32 s10, s10, s58
	s_lshl_b32 s11, s7, 6
	s_mul_i32 s59, s10, s91
	s_add_i32 s59, s59, s11
	s_lshl_b32 s59, s59, 2
	s_add_u32 s50, s50, s59
	s_addc_u32 s51, s51, 0
	s_mul_i32 s59, s11, s90
	s_add_i32 s59, s59, s10
	s_lshl_b32 s59, s59, 1
	s_add_u32 s56, s56, s59
	s_addc_u32 s57, s57, 0
	s_add_u32 s56, s56, vcc_lo
	s_addc_u32 s57, s57, vcc_hi
	v_mul_u32_u24_e32 v78, s90, v29
	s_lshl_b32 s91, s91, 2
	global_load_dword v46, v26, s[50:51] nt
	s_add_u32 s50, s50, s91
	s_addc_u32 s51, s51, 0
	global_load_dword v47, v26, s[50:51] nt
	s_add_u32 s50, s50, s91
	s_addc_u32 s51, s51, 0
	global_load_dword v48, v26, s[50:51] nt
	s_add_u32 s50, s50, s91
	s_addc_u32 s51, s51, 0
	global_load_dword v49, v26, s[50:51] nt
	s_add_u32 s50, s50, s91
	s_addc_u32 s51, s51, 0
	global_load_dword v50, v26, s[50:51] nt
	s_add_u32 s50, s50, s91
	s_addc_u32 s51, s51, 0
	global_load_dword v51, v26, s[50:51] nt
	s_add_u32 s50, s50, s91
	s_addc_u32 s51, s51, 0
	global_load_dword v52, v26, s[50:51] nt
	s_add_u32 s50, s50, s91
	s_addc_u32 s51, s51, 0
	global_load_dword v53, v26, s[50:51] nt
	s_add_u32 s50, s50, s91
	s_addc_u32 s51, s51, 0
	global_load_dword v54, v26, s[50:51] nt
	s_add_u32 s50, s50, s91
	s_addc_u32 s51, s51, 0
	global_load_dword v55, v26, s[50:51] nt
	s_add_u32 s50, s50, s91
	s_addc_u32 s51, s51, 0
	global_load_dword v56, v26, s[50:51] nt
	s_add_u32 s50, s50, s91
	s_addc_u32 s51, s51, 0
	global_load_dword v57, v26, s[50:51] nt
	s_add_u32 s50, s50, s91
	s_addc_u32 s51, s51, 0
	global_load_dword v58, v26, s[50:51] nt
	s_add_u32 s50, s50, s91
	s_addc_u32 s51, s51, 0
	global_load_dword v59, v26, s[50:51] nt
	s_add_u32 s50, s50, s91
	s_addc_u32 s51, s51, 0
	global_load_dword v60, v26, s[50:51] nt
	s_add_u32 s50, s50, s91
	s_addc_u32 s51, s51, 0
	global_load_dword v61, v26, s[50:51] nt
